# gemm loop next-segment setup after barrier; 16-byte stores write-through; norm rows dealt wave-major across workgroups
# baseline (speedup 1.0000x reference)
; __device__ __forceinline__ int otid() { int t = threadIdx.x; asm volatile("" : "+v"(t)); return t; }
; __device__ __forceinline__ void norm_phase(float* __restrict__ X, bf16_t* __restrict__ H, const float* __restrict__ modl, int shiftIdx, int scaleIdx, int nrows, const float* __restrict__ PART, const float* __restrict__ XLAT) {
;     const int tid_ = otid(); const int lane = tid_ & 63, gw = blockIdx.x * 8 + (tid_ >> 6), nw = gridDim.x * 8;
;     for (int row = gw; row < nrows; row += nw) {
;         float* xr = X + (size_t)row * DM;
;         const float* xs = (XLAT != nullptr && row < NLAT) ? XLAT + (size_t)row * DM : xr;
;         f32x4 x[8]; float ss = 0.f;
; #pragma unroll
;         for (int i = 0; i < 8; ++i) x[i] = *(const f32x4*)(xs + (i * 64 + lane) * 4);
;         if (PART != nullptr && row >= NLAT) {
; #pragma unroll
;             for (int s = 0; s < 8; ++s) { f32x4 pt[8];
; #pragma unroll
;                 for (int i = 0; i < 8; ++i) pt[i] = *(const f32x4*)(PART + ((size_t)s * NCTX + (row - NLAT)) * DM + (i * 64 + lane) * 4);
; #pragma unroll
;                 for (int i = 0; i < 8; ++i) x[i] += pt[i]; }
; #pragma unroll
;             for (int i = 0; i < 8; ++i) *(f32x4*)(xr + (i * 64 + lane) * 4) = x[i];
;         }
; #pragma unroll
;         for (int i = 0; i < 8; ++i) ss += x[i][0] * x[i][0] + x[i][1] * x[i][1] + x[i][2] * x[i][2] + x[i][3] * x[i][3];
;         ss = wave_sum(ss);
;         const float r = rsqrtf(ss * (1.f / DM) + EPS);
;         const int v = row < NLAT ? (row >> 11) : 4;
;         const float* sh = modl + (size_t)v * MODW + shiftIdx * DM; const float* scl = modl + (size_t)v * MODW + scaleIdx * DM;
; #pragma unroll
;         for (int i = 0; i < 8; ++i) { const int c = (i * 64 + lane) * 4; const f32x4 s4 = *(const f32x4*)(sh + c), c4 = *(const f32x4*)(scl + c);
.LBB0_2146:
	s_mul_i32 s0, s4, 12
	v_writelane_b32 v255, s0, 56
	s_or_b32 s2, s0, 2
	s_mov_b32 s0, s4
	v_writelane_b32 v255, s0, 57
	s_nop 1
	v_writelane_b32 v255, s1, 58
	s_mul_i32 s0, s4, 0x5a000
	v_readlane_b32 s1, v251, 24
	s_add_u32 s6, s1, s0
	v_readlane_b32 s0, v251, 25
	s_addc_u32 s7, s0, 0
	s_cmp_le_i32 s94, s2
	s_cselect_b64 s[0:1], -1, 0
	s_cmp_lt_i32 s2, s95
	s_cselect_b64 s[2:3], -1, 0
	v_writelane_b32 v255, s6, 59
	s_and_b64 s[2:3], s[0:1], s[2:3]
	s_andn2_b64 vcc, exec, s[2:3]
	v_writelane_b32 v255, s7, 60
	s_cbranch_vccnz .LBB0_2153
	v_mov_b32_e32 v0, v176
	v_readlane_b32 s2, v251, 48
	v_ashrrev_i32_e32 v1, 6, v0
	v_mul_lo_u32 v1, v1, s96
	s_nop 0
	v_lshrrev_b32_e64 v32, 3, s2
	v_add_u32_e32 v32, v32, v1
	s_movk_i32 s2, 0x2400
	v_cmp_gt_i32_e32 vcc, s2, v32
	s_and_saveexec_b64 s[2:3], vcc
	s_cbranch_execz .LBB0_2152
	v_readlane_b32 s6, v251, 26
	v_readlane_b32 s7, v251, 27
	s_and_b64 s[10:11], s[6:7], s[38:39]
	s_and_b64 s[6:7], s[10:11], exec
	v_readlane_b32 s6, v251, 46
	v_lshlrev_b32_e32 v1, 2, v0
	v_cmp_lt_i32_e32 vcc, v250, v214
	v_readlane_b32 s7, v251, 47
	v_and_b32_e32 v34, 0xfc, v1
	v_cndmask_b32_e32 v1, v213, v250, vcc
	v_cmp_lt_i32_e32 vcc, v219, v214
	s_cselect_b32 s39, s7, 0
	s_cselect_b32 s38, s6, 0
	v_readlane_b32 s6, v255, 51
	v_lshlrev_b32_e32 v35, 2, v1
	v_cndmask_b32_e32 v1, v213, v219, vcc
	v_cmp_lt_i32_e32 vcc, v218, v214
	v_readlane_b32 s7, v255, 52
	v_readlane_b32 s40, v251, 28
	v_lshlrev_b32_e32 v66, 2, v1
	v_cndmask_b32_e32 v1, v213, v218, vcc
	v_cmp_lt_i32_e32 vcc, v217, v214
	s_and_b64 s[6:7], s[6:7], exec
	v_readlane_b32 s41, v251, 29
	v_lshlrev_b32_e32 v67, 2, v1
	v_cndmask_b32_e32 v1, v213, v217, vcc
	v_cmp_lt_i32_e32 vcc, v216, v214
	s_cselect_b32 s41, s41, 0
	s_cselect_b32 s40, s40, 0
	v_lshlrev_b32_e32 v68, 2, v1
	v_cndmask_b32_e32 v1, v213, v216, vcc
	v_cmp_lt_i32_e32 vcc, v215, v214
	v_ashrrev_i32_e32 v33, 31, v32
	v_readlane_b32 s42, v251, 30
	v_readlane_b32 s43, v251, 31
	v_readlane_b32 s44, v251, 32
	v_readlane_b32 s45, v251, 33
	s_cmp_lg_u64 s[40:41], 0
	v_lshlrev_b32_e32 v69, 2, v1
	v_cndmask_b32_e32 v1, v213, v215, vcc
	v_or_b32_e32 v2, 0x100, v34
	v_or_b32_e32 v4, 0x200, v34
	v_or_b32_e32 v6, 0x300, v34
	v_or_b32_e32 v8, 0x400, v34
	v_or_b32_e32 v10, 0x500, v34
	v_or_b32_e32 v12, 0x600, v34
	v_or_b32_e32 v14, 0x700, v34
	v_lshlrev_b64 v[36:37], 12, v[32:33]
	v_and_b32_e32 v0, 63, v0
	v_lshlrev_b64 v[38:39], 13, v[32:33]
	s_mov_b64 s[42:43], 0
	s_cselect_b64 s[44:45], -1, 0
	v_lshlrev_b32_e32 v70, 2, v1
	v_lshl_or_b32 v36, v0, 3, v36
	v_lshl_or_b32 v38, v0, 4, v38
	v_lshlrev_b32_e32 v40, 2, v2
	v_lshlrev_b32_e32 v42, 2, v4
	v_lshlrev_b32_e32 v44, 2, v6
	v_lshlrev_b32_e32 v46, 2, v8
	v_lshlrev_b32_e32 v48, 2, v10
	v_lshlrev_b32_e32 v50, 2, v12
	v_lshlrev_b32_e32 v52, 2, v14
	v_readlane_b32 s46, v251, 34
	v_readlane_b32 s47, v251, 35
	v_readlane_b32 s48, v251, 36
	v_readlane_b32 s49, v251, 37
	v_readlane_b32 s50, v251, 38
	v_readlane_b32 s51, v251, 39
	v_readlane_b32 s52, v251, 40
	v_readlane_b32 s53, v251, 41
	v_readlane_b32 s54, v251, 42
	v_readlane_b32 s55, v251, 43
	s_branch .LBB0_2150

; __device__ __forceinline__ int otid() { int t = threadIdx.x; asm volatile("" : "+v"(t)); return t; }
; __device__ __forceinline__ void norm_phase(float* __restrict__ X, bf16_t* __restrict__ H, const float* __restrict__ modl, int shiftIdx, int scaleIdx, int nrows, const float* __restrict__ PART, const float* __restrict__ XLAT) {
;     const int tid_ = otid(); const int lane = tid_ & 63, gw = blockIdx.x * 8 + (tid_ >> 6), nw = gridDim.x * 8;
;     for (int row = gw; row < nrows; row += nw) {
;         float* xr = X + (size_t)row * DM;
;         const float* xs = (XLAT != nullptr && row < NLAT) ? XLAT + (size_t)row * DM : xr;
;         f32x4 x[8]; float ss = 0.f;
; #pragma unroll
;         for (int i = 0; i < 8; ++i) x[i] = *(const f32x4*)(xs + (i * 64 + lane) * 4);
.LBB0_2651:
	s_cmp_le_i32 s94, s4
	s_cselect_b64 s[0:1], -1, 0
	s_and_b64 s[2:3], s[0:1], s[10:11]
	s_andn2_b64 vcc, exec, s[2:3]
	s_cbranch_vccnz .LBB0_2658
	v_mov_b32_e32 v0, v176
	v_readlane_b32 s2, v251, 48
	v_ashrrev_i32_e32 v1, 6, v0
	v_mul_lo_u32 v1, v1, s96
	s_nop 0
	v_lshrrev_b32_e64 v32, 3, s2
	v_add_u32_e32 v32, v32, v1
	s_movk_i32 s2, 0x2400
	v_cmp_gt_i32_e32 vcc, s2, v32
	s_and_saveexec_b64 s[2:3], vcc
	s_cbranch_execz .LBB0_2657
	v_lshlrev_b32_e32 v1, 2, v0
	v_cmp_lt_i32_e32 vcc, v250, v214
	v_and_b32_e32 v34, 0xfc, v1
	v_ashrrev_i32_e32 v33, 31, v32
	v_cndmask_b32_e32 v1, v213, v250, vcc
	v_cmp_lt_i32_e32 vcc, v219, v214
	v_lshlrev_b32_e32 v35, 2, v1
	v_or_b32_e32 v2, 0x100, v34
	v_cndmask_b32_e32 v1, v213, v219, vcc
	v_cmp_lt_i32_e32 vcc, v218, v214
	v_lshlrev_b32_e32 v104, 2, v1
	v_or_b32_e32 v4, 0x200, v34
	v_cndmask_b32_e32 v1, v213, v218, vcc
	v_cmp_lt_i32_e32 vcc, v217, v214
	v_lshlrev_b32_e32 v105, 2, v1
	v_or_b32_e32 v6, 0x300, v34
	v_cndmask_b32_e32 v1, v213, v217, vcc
	v_cmp_lt_i32_e32 vcc, v216, v214
	v_lshlrev_b32_e32 v106, 2, v1
	v_or_b32_e32 v8, 0x400, v34
	v_cndmask_b32_e32 v1, v213, v216, vcc
	v_cmp_lt_i32_e32 vcc, v215, v214
	v_lshlrev_b32_e32 v107, 2, v1
	v_or_b32_e32 v10, 0x500, v34
	v_cndmask_b32_e32 v1, v213, v215, vcc
	v_or_b32_e32 v12, 0x600, v34
	v_or_b32_e32 v14, 0x700, v34
	v_lshlrev_b64 v[36:37], 12, v[32:33]
	v_and_b32_e32 v0, 63, v0
	v_lshlrev_b64 v[38:39], 13, v[32:33]
	v_lshlrev_b32_e32 v108, 2, v1
	v_lshl_or_b32 v36, v0, 3, v36
	v_lshl_or_b32 v38, v0, 4, v38
	s_mov_b64 s[10:11], 0
	v_lshlrev_b32_e32 v40, 2, v2
	v_lshlrev_b32_e32 v42, 2, v4
	v_lshlrev_b32_e32 v44, 2, v6
	v_lshlrev_b32_e32 v46, 2, v8
	v_lshlrev_b32_e32 v48, 2, v10
	v_lshlrev_b32_e32 v50, 2, v12
	v_lshlrev_b32_e32 v52, 2, v14
	s_branch .LBB0_2655

; __device__ __forceinline__ int otid() { int t = threadIdx.x; asm volatile("" : "+v"(t)); return t; }
; __device__ __forceinline__ void norm_phase(float* __restrict__ X, bf16_t* __restrict__ H, const float* __restrict__ modl, int shiftIdx, int scaleIdx, int nrows, const float* __restrict__ PART, const float* __restrict__ XLAT) {
;     const int tid_ = otid(); const int lane = tid_ & 63, gw = blockIdx.x * 8 + (tid_ >> 6), nw = gridDim.x * 8;
;     for (int row = gw; row < nrows; row += nw) {
;         float* xr = X + (size_t)row * DM;
;         const float* xs = (XLAT != nullptr && row < NLAT) ? XLAT + (size_t)row * DM : xr;
;         f32x4 x[8]; float ss = 0.f;
; #pragma unroll
;         for (int i = 0; i < 8; ++i) x[i] = *(const f32x4*)(xs + (i * 64 + lane) * 4);
.LBB0_3646:
	v_readlane_b32 s0, v255, 51
	v_readlane_b32 s1, v255, 52
	s_and_b64 s[0:1], s[0:1], exec
	s_movk_i32 s0, 0x2000
	s_cselect_b32 s4, 0x2400, s0
	s_cmp_le_i32 s94, s6
	s_cselect_b64 s[0:1], -1, 0
	s_and_b64 s[2:3], s[0:1], s[2:3]
	s_andn2_b64 vcc, exec, s[2:3]
	s_cbranch_vccnz .LBB0_3653
	v_mov_b32_e32 v0, v176
	v_readlane_b32 s2, v251, 48
	v_ashrrev_i32_e32 v1, 6, v0
	v_mul_lo_u32 v1, v1, s96
	s_nop 0
	v_lshrrev_b32_e64 v32, 3, s2
	v_add_u32_e32 v32, v32, v1
	v_cmp_gt_i32_e32 vcc, s4, v32
	s_and_saveexec_b64 s[2:3], vcc
	s_cbranch_execz .LBB0_3652
	v_lshlrev_b32_e32 v1, 2, v0
	v_cmp_lt_i32_e32 vcc, v250, v214
	v_readlane_b32 s6, v255, 51
	v_readlane_b32 s22, v251, 26
	v_and_b32_e32 v34, 0xfc, v1
	v_cndmask_b32_e32 v1, v213, v250, vcc
	v_cmp_lt_i32_e32 vcc, v219, v214
	v_readlane_b32 s7, v255, 52
	v_readlane_b32 s23, v251, 27
	v_lshlrev_b32_e32 v35, 2, v1
	v_cndmask_b32_e32 v1, v213, v219, vcc
	v_cmp_lt_i32_e32 vcc, v218, v214
	s_and_b64 s[38:39], s[22:23], s[6:7]
	v_lshlrev_b32_e32 v104, 2, v1
	v_cndmask_b32_e32 v1, v213, v218, vcc
	v_cmp_lt_i32_e32 vcc, v217, v214
	s_and_b64 s[6:7], s[38:39], exec
	v_lshlrev_b32_e32 v105, 2, v1
	v_cndmask_b32_e32 v1, v213, v217, vcc
	v_cmp_lt_i32_e32 vcc, v216, v214
	v_readlane_b32 s6, v251, 46
	v_lshlrev_b32_e32 v106, 2, v1
	v_cndmask_b32_e32 v1, v213, v216, vcc
	v_cmp_lt_i32_e32 vcc, v215, v214
	v_ashrrev_i32_e32 v33, 31, v32
	v_readlane_b32 s7, v251, 47
	v_lshlrev_b32_e32 v107, 2, v1
	v_cndmask_b32_e32 v1, v213, v215, vcc
	v_or_b32_e32 v2, 0x100, v34
	v_or_b32_e32 v4, 0x200, v34
	v_or_b32_e32 v6, 0x300, v34
	v_or_b32_e32 v8, 0x400, v34
	v_or_b32_e32 v10, 0x500, v34
	v_or_b32_e32 v12, 0x600, v34
	v_or_b32_e32 v14, 0x700, v34
	v_lshlrev_b64 v[36:37], 12, v[32:33]
	v_and_b32_e32 v0, 63, v0
	v_lshlrev_b64 v[38:39], 13, v[32:33]
	s_cselect_b32 s41, s7, 0
	s_cselect_b32 s40, s6, 0
	v_lshlrev_b32_e32 v108, 2, v1
	v_lshl_or_b32 v36, v0, 3, v36
	v_lshl_or_b32 v38, v0, 4, v38
	s_mov_b64 s[42:43], 0
	v_lshlrev_b32_e32 v40, 2, v2
	v_lshlrev_b32_e32 v42, 2, v4
	v_lshlrev_b32_e32 v44, 2, v6
	v_lshlrev_b32_e32 v46, 2, v8
	v_lshlrev_b32_e32 v48, 2, v10
	v_lshlrev_b32_e32 v50, 2, v12
	v_lshlrev_b32_e32 v52, 2, v14
	s_branch .LBB0_3650
